# P9 conv epilogue: first-needed weight vectors of the next unit prefetched at the end of the epilogue into registers that survive the k-loop
# baseline (speedup 1.0000x reference)
;     __device__ __forceinline__ bool next(int i, Unit& u) const { return decode(i * G + c, u); }
; #define PG8_STAGE(bufoff, gbase, voff) do { _Pragma("unroll") for (int _i = 0; _i < 2; ++_i) \
;         __builtin_amdgcn_global_load_lds((const unsigned*)((const char*)(gbase) + (voff)[_i]), (LAS unsigned*)(lds + (bufoff) + ldsw + _i * 8192), 16, 0, 0); } while (0)
; #define PG8_WAIT_V(n) asm volatile("s_waitcnt vmcnt(" #n ")" ::: "memory")
; #define PG8_BAR __builtin_amdgcn_s_barrier()
; template <class Epi, class Sched, bool DEFER>
; __device__ __forceinline__ void gemm_fast_core(LAS unsigned char* lds, const GemmP g, const Sched& S, const Epi& E, f32x4 (&acc)[2][2][4][2], Unit& cur) {
;     ...
;     const int wid = __builtin_amdgcn_readfirstlane(tid >> 6), lane = tid & 63, wr = wid >> 2, wc = wid & 3, fr = lane & 15, fq = lane >> 4;
;     const int K = g.K, nt = K / BK;
;     unsigned voffA[2], voffB[2];
; #pragma unroll
;     for (int i = 0; i < 2; ++i) { int R, C; stage_rc(tid * 16 + i * 8192, R, C); voffA[i] = (unsigned)(R * g.lda + C) * 2u; voffB[i] = (unsigned)(R * g.ldb + C) * 2u; }
;     const size_t kstep = (size_t)(BK * 2);
;     const size_t hstepA = (size_t)HALF * g.lda * 2, hstepB = (size_t)HALF * g.ldb * 2;
;     const unsigned ldsw = (unsigned)wid * 1024u;
;     const int aoff = lds_byte(wr * 64 + fr, fq * 8), boff = lds_byte(wc * 32 + fr, fq * 8);
;     ...
;     Unit nxt; int ui = 0;
;     if (!S.next(0, cur)) return;
; #pragma unroll
;     for (int a = 0; a < 2; ++a)
; #pragma unroll
;         for (int b = 0; b < 2; ++b)
; #pragma unroll
;             for (int m = 0; m < 4; ++m)
; #pragma unroll
;                 for (int n = 0; n < 2; ++n) acc[a][b][m][n] = (f32x4){0.f, 0.f, 0.f, 0.f};
;     bf16x8 At[4][2], B0[2][2], B1[2][2];
;     const char* cA = (const char*)g.aptr(cur); const char* cB = (const char*)g.bptr(cur);
;     PG8_STAGE(PG8_SB(0, 0), cB, voffB); PG8_STAGE(PG8_SB(0, 1), cB + hstepB, voffB); PG8_STAGE(PG8_SA(0, 0), cA, voffA); PG8_STAGE(PG8_SA(0, 1), cA + hstepA, voffA);
;     if (wr == 1) PG8_BAR;
;     PG8_WAIT_V(2); PG8_BAR;
;     PG8_STAGE(PG8_SB(1, 0), cB + kstep, voffB); PG8_STAGE(PG8_SA(1, 0), cA + kstep, voffA); PG8_STAGE(PG8_SB(1, 1), cB + hstepB + kstep, voffB);
;     PG8_WAIT_V(6); PG8_BAR;
;     for (;;) {
.LBB0_1793:
	s_lshl_b32 s7, s7, 5
	s_mov_b64 s[8:9], 0x80
	s_and_b32 s16, s7, 0x60
	s_add_i32 m0, s27, 0x18000
	v_lshl_add_u64 v[6:7], v[6:7], 0, s[8:9]
	s_lshl_b32 s12, s6, 13
	s_lshl_b32 s7, s16, 7
	s_waitcnt vmcnt(2)
	s_barrier
	global_load_lds_dwordx4 v[6:7], off
	v_lshl_add_u64 v[4:5], v[4:5], 0, s[8:9]
	s_add_i32 m0, s27, 0x1a000
	s_add_i32 s42, s27, 0x8000
	s_add_i32 s43, s27, 0xa000
	global_load_lds_dwordx4 v[4:5], off
	v_lshl_add_u64 v[0:1], v[0:1], 0, s[8:9]
	s_mov_b32 m0, s42
	s_add_u32 s10, s30, 0x80080
	global_load_lds_dwordx4 v[0:1], off
	v_lshl_add_u64 v[0:1], v[2:3], 0, s[8:9]
	s_mov_b32 m0, s43
	s_addc_u32 s11, s31, 0
	global_load_lds_dwordx4 v[0:1], off
	s_add_i32 m0, s27, 0x1c000
	v_lshl_add_u64 v[0:1], s[10:11], 0, v[162:163]
	global_load_lds_dwordx4 v[0:1], off
	v_lshl_add_u64 v[0:1], s[10:11], 0, v[160:161]
	s_add_i32 m0, s27, 0x1e000
	v_lshlrev_b32_e32 v3, 2, v11
	global_load_lds_dwordx4 v[0:1], off
	v_bfe_u32 v1, v11, 4, 2
	v_and_b32_e32 v0, 15, v11
	v_lshlrev_b32_e32 v2, 4, v1
	v_lshl_or_b32 v2, v0, 6, v2
	v_and_b32_e32 v3, 32, v3
	s_sext_i32_i16 s33, s4
	v_lshl_or_b32 v195, s6, 6, v0
	v_bitop3_b32 v196, v2, s7, v3 bitop3:0xde
	s_cmpk_lt_u32 s5, 0x100
	v_cmp_eq_u32_e64 s[4:5], 15, v0
	v_cmp_eq_u32_e64 s[6:7], 0, v0
	v_lshlrev_b32_e32 v0, 15, v12
	v_and_b32_e32 v0, 0xffff0000, v0
	v_lshl_or_b32 v204, v1, 2, s16
	v_lshl_add_u32 v0, v13, 12, v0
	v_and_b32_e32 v1, 1, v12
	v_lshl_or_b32 v0, v1, 6, v0
	v_bitop3_b32 v4, v2, s12, v3 bitop3:0xde
	s_cselect_b64 s[10:11], -1, 0
	s_add_u32 s12, s56, 0xb000
	v_lshl_add_u32 v164, v14, 1, v0
	v_lshlrev_b32_e32 v0, 15, v8
	s_addc_u32 s13, s57, 0
	v_and_b32_e32 v0, 0xffff0000, v0
	s_waitcnt vmcnt(6)
	s_add_u32 s14, s56, 0x16000
	v_lshl_add_u32 v0, v9, 12, v0
	v_and_b32_e32 v1, 1, v8
	s_addc_u32 s15, s57, 0
	v_lshl_or_b32 v0, v1, 6, v0
	s_add_i32 s44, 0, 0x10000
	s_add_i32 s45, 0, 0x14000
	v_or_b32_e32 v197, 16, v195
	v_or_b32_e32 v198, 32, v195
	v_or_b32_e32 v199, 48, v195
	v_add_u32_e32 v200, 0x80, v195
	v_add_u32_e32 v201, 0x90, v195
	v_add_u32_e32 v202, 0xa0, v195
	v_add_u32_e32 v203, 0xb0, v195
	v_mov_b32_e32 v165, v163
	v_lshl_add_u32 v166, v10, 1, v0
	v_mov_b32_e32 v167, v163
	v_add_u32_e32 v164, v164, v188
	v_add_u32_e32 v166, v166, v188
	v_add_u32_e32 v205, s44, v196
	v_add_u32_e32 v206, s45, v196
	v_add_u32_e32 v207, 0, v4
	s_movk_i32 s46, 0x2c00
	s_barrier
	s_mov_b32 s98, 0
	s_branch .LBB0_1796

; __device__ __forceinline__ float dpp_ror1(float v) { return __int_as_float(__builtin_amdgcn_update_dpp(0, __float_as_int(v), 0x121, 0xf, 0xf, false)); }
; __device__ __forceinline__ float dpp_rol1(float v) { return __int_as_float(__builtin_amdgcn_update_dpp(0, __float_as_int(v), 0x12F, 0xf, 0xf, false)); }
;     __device__ __forceinline__ void tile(const f32x4 (&acc)[2][2][4][2], const Unit& u, int wr, int wc, int fr, int fq) const {
;     ...
;             const int cv = 128 * u.pn + 32 * wc + 16 * n + 4 * fq, cg = FF + cv;
;             const f32x4 wv0 = *(const f32x4*)(cw + cv), wv1 = *(const f32x4*)(cw + F2 + cv), wv2 = *(const f32x4*)(cw + 2 * F2 + cv), bv = *(const f32x4*)(cb + cv);
;             const f32x4 wg0 = *(const f32x4*)(cw + cg), wg1 = *(const f32x4*)(cw + F2 + cg), wg2 = *(const f32x4*)(cw + 2 * F2 + cg), bg = *(const f32x4*)(cb + cg);
; #pragma unroll
;             for (int ai = 0; ai < 2; ++ai)
; #pragma unroll
;                 for (int m = 0; m < 4; ++m) {
;                     f32x4 r;
; #pragma unroll
;                     for (int i = 0; i < 4; ++i) {
;                         const float xv = acc[ai][0][m][n][i], xg = acc[ai][1][m][n][i];
;                         const float uv = m > 0 ? acc[ai][0][m > 0 ? m - 1 : 0][n][i] : 0.f, ug = m > 0 ? acc[ai][1][m > 0 ? m - 1 : 0][n][i] : 0.f;
;                         const float dv = m < 3 ? acc[ai][0][m < 3 ? m + 1 : 3][n][i] : 0.f, dg = m < 3 ? acc[ai][1][m < 3 ? m + 1 : 3][n][i] : 0.f;
;                         const float pv = dpp_ror1(fr == 15 ? uv : xv), pg = dpp_ror1(fr == 15 ? ug : xg);
;                         const float nv = dpp_rol1(fr == 0 ? dv : xv), ng = dpp_rol1(fr == 0 ? dg : xg);
;                         const float yv = wv0[i] * pv + wv1[i] * xv + wv2[i] * nv + bv[i];
;                         const float yg = wg0[i] * pg + wg1[i] * xg + wg2[i] * ng + bg[i];
.LBB0_1802:
	v_lshl_or_b32 v170, s33, 7, v204
	v_lshlrev_b32_e32 v171, 2, v170
	v_add_u32_e32 v172, 0x5800, v171
	s_cmp_lg_u32 s98, 0
	s_cbranch_scc1 .Lp9c_havepre
	global_load_dwordx4 v[230:233], v172, s[56:57]
	global_load_dwordx4 v[234:237], v172, s[12:13]
	global_load_dwordx4 v[238:241], v172, s[14:15]
	global_load_dwordx4 v[242:245], v172, s[58:59]
	global_load_dwordx4 v[246:249], v171, s[56:57]
	global_load_dwordx4 v[250:253], v171, s[12:13]
.Lp9c_havepre:
	global_load_dwordx4 v[120:123], v171, s[14:15]
	global_load_dwordx4 v[124:127], v171, s[58:59]
	global_load_dwordx4 v[128:131], v172, s[56:57] offset:64
	global_load_dwordx4 v[132:135], v172, s[12:13] offset:64
	global_load_dwordx4 v[136:139], v172, s[14:15] offset:64
	global_load_dwordx4 v[140:143], v172, s[58:59] offset:64
	global_load_dwordx4 v[144:147], v171, s[56:57] offset:64
	global_load_dwordx4 v[148:151], v171, s[12:13] offset:64
	global_load_dwordx4 v[208:211], v171, s[14:15] offset:64
	global_load_dwordx4 v[212:215], v171, s[58:59] offset:64
	s_lshl_b32 s17, s26, 8
	v_and_b32_e32 v173, 64, v195
	v_and_b32_e32 v174, 15, v195
	v_lshl_add_u32 v173, v174, 2, v173
	v_add_u32_e32 v173, s17, v173
	v_mul_u32_u24_e32 v173, 0x2c00, v173
	v_lshl_add_u32 v173, v170, 1, v173
	v_add_u32_e32 v174, 0x160000, v173
	s_waitcnt vmcnt(12)
	v_mov_b32_dpp v216, v96 row_shr:1 row_mask:0xf bank_mask:0xf bound_ctrl:1
	v_mov_b32_dpp v217, v97 row_shr:1 row_mask:0xf bank_mask:0xf bound_ctrl:1
	v_mov_b32_dpp v218, v98 row_shr:1 row_mask:0xf bank_mask:0xf bound_ctrl:1
	v_mov_b32_dpp v219, v99 row_shr:1 row_mask:0xf bank_mask:0xf bound_ctrl:1
	v_mov_b32_dpp v220, v152 row_shl:1 row_mask:0xf bank_mask:0xf bound_ctrl:1
	v_mov_b32_dpp v221, v153 row_shl:1 row_mask:0xf bank_mask:0xf bound_ctrl:1
	v_mov_b32_dpp v222, v154 row_shl:1 row_mask:0xf bank_mask:0xf bound_ctrl:1
	v_mov_b32_dpp v223, v155 row_shl:1 row_mask:0xf bank_mask:0xf bound_ctrl:1
	v_pk_mul_f32 v[176:177], v[152:153], v[234:235]
	v_pk_mul_f32 v[178:179], v[154:155], v[236:237]
	v_pk_mul_f32 v[180:181], v[112:113], v[234:235]
	v_pk_mul_f32 v[182:183], v[114:115], v[236:237]
	v_pk_mul_f32 v[184:185], v[104:105], v[234:235]
	v_pk_mul_f32 v[186:187], v[106:107], v[236:237]
	v_pk_mul_f32 v[224:225], v[96:97], v[234:235]
	v_pk_mul_f32 v[226:227], v[98:99], v[236:237]
	v_pk_fma_f32 v[176:177], v[230:231], v[216:217], v[176:177]
	v_pk_fma_f32 v[178:179], v[232:233], v[218:219], v[178:179]
	v_pk_fma_f32 v[180:181], v[230:231], v[152:153], v[180:181]
	v_pk_fma_f32 v[182:183], v[232:233], v[154:155], v[182:183]
	v_pk_fma_f32 v[184:185], v[230:231], v[112:113], v[184:185]
	v_pk_fma_f32 v[186:187], v[232:233], v[114:115], v[186:187]
	v_pk_fma_f32 v[224:225], v[230:231], v[104:105], v[224:225]
	v_pk_fma_f32 v[226:227], v[232:233], v[106:107], v[226:227]
	v_pk_fma_f32 v[176:177], v[238:239], v[112:113], v[176:177]
	v_pk_fma_f32 v[178:179], v[240:241], v[114:115], v[178:179]
	v_pk_fma_f32 v[180:181], v[238:239], v[104:105], v[180:181]
	v_pk_fma_f32 v[182:183], v[240:241], v[106:107], v[182:183]
	v_pk_fma_f32 v[184:185], v[238:239], v[96:97], v[184:185]
	v_pk_fma_f32 v[186:187], v[240:241], v[98:99], v[186:187]
	v_pk_fma_f32 v[224:225], v[238:239], v[220:221], v[224:225]
	v_pk_fma_f32 v[226:227], v[240:241], v[222:223], v[226:227]
	v_pk_add_f32 v[176:177], v[242:243], v[176:177]
	v_pk_add_f32 v[178:179], v[244:245], v[178:179]
	v_pk_add_f32 v[180:181], v[242:243], v[180:181]
	v_pk_add_f32 v[182:183], v[244:245], v[182:183]
	v_pk_add_f32 v[184:185], v[242:243], v[184:185]
	v_pk_add_f32 v[186:187], v[244:245], v[186:187]
	v_pk_add_f32 v[224:225], v[242:243], v[224:225]
	v_pk_add_f32 v[226:227], v[244:245], v[226:227]
	s_waitcnt vmcnt(8)
	v_mov_b32_dpp v216, v100 row_shr:1 row_mask:0xf bank_mask:0xf bound_ctrl:1
	v_mov_b32_dpp v217, v101 row_shr:1 row_mask:0xf bank_mask:0xf bound_ctrl:1
	v_mov_b32_dpp v218, v102 row_shr:1 row_mask:0xf bank_mask:0xf bound_ctrl:1
	v_mov_b32_dpp v219, v103 row_shr:1 row_mask:0xf bank_mask:0xf bound_ctrl:1
	v_mov_b32_dpp v220, v156 row_shl:1 row_mask:0xf bank_mask:0xf bound_ctrl:1
	v_mov_b32_dpp v221, v157 row_shl:1 row_mask:0xf bank_mask:0xf bound_ctrl:1
	v_mov_b32_dpp v222, v158 row_shl:1 row_mask:0xf bank_mask:0xf bound_ctrl:1
	v_mov_b32_dpp v223, v159 row_shl:1 row_mask:0xf bank_mask:0xf bound_ctrl:1
	v_pk_mul_f32 v[152:153], v[156:157], v[250:251]
	v_pk_mul_f32 v[154:155], v[158:159], v[252:253]
	v_pk_mul_f32 v[112:113], v[116:117], v[250:251]
	v_pk_mul_f32 v[114:115], v[118:119], v[252:253]
	v_pk_mul_f32 v[104:105], v[108:109], v[250:251]
	v_pk_mul_f32 v[106:107], v[110:111], v[252:253]
	v_pk_mul_f32 v[96:97], v[100:101], v[250:251]
	v_pk_mul_f32 v[98:99], v[102:103], v[252:253]
	v_pk_fma_f32 v[152:153], v[246:247], v[216:217], v[152:153]
	v_pk_fma_f32 v[154:155], v[248:249], v[218:219], v[154:155]
	v_pk_fma_f32 v[112:113], v[246:247], v[156:157], v[112:113]
	v_pk_fma_f32 v[114:115], v[248:249], v[158:159], v[114:115]
	v_pk_fma_f32 v[104:105], v[246:247], v[116:117], v[104:105]
	v_pk_fma_f32 v[106:107], v[248:249], v[118:119], v[106:107]
	v_pk_fma_f32 v[96:97], v[246:247], v[108:109], v[96:97]
	v_pk_fma_f32 v[98:99], v[248:249], v[110:111], v[98:99]
	v_pk_fma_f32 v[152:153], v[120:121], v[116:117], v[152:153]
	v_pk_fma_f32 v[154:155], v[122:123], v[118:119], v[154:155]
	v_pk_fma_f32 v[112:113], v[120:121], v[108:109], v[112:113]
	v_pk_fma_f32 v[114:115], v[122:123], v[110:111], v[114:115]
	v_pk_fma_f32 v[104:105], v[120:121], v[100:101], v[104:105]
	v_pk_fma_f32 v[106:107], v[122:123], v[102:103], v[106:107]
	v_pk_fma_f32 v[96:97], v[120:121], v[220:221], v[96:97]
	v_pk_fma_f32 v[98:99], v[122:123], v[222:223], v[98:99]
; __device__ __forceinline__ void st_bf4(bf16_t* p, f32x4 v) { u32x2 w; w.x = pk2(v[0], v[1]); w.y = pk2(v[2], v[3]); *(u32x2*)p = w; }
; __device__ __forceinline__ float sigmoidf_(float x) { return __builtin_amdgcn_rcpf(1.f + __expf(-x)); }
; __device__ __forceinline__ float dpp_ror1(float v) { return __int_as_float(__builtin_amdgcn_update_dpp(0, __float_as_int(v), 0x121, 0xf, 0xf, false)); }
; __device__ __forceinline__ float dpp_rol1(float v) { return __int_as_float(__builtin_amdgcn_update_dpp(0, __float_as_int(v), 0x12F, 0xf, 0xf, false)); }
;     __device__ __forceinline__ void tile(const f32x4 (&acc)[2][2][4][2], const Unit& u, int wr, int wc, int fr, int fq) const {
;     ...
;                     for (int i = 0; i < 4; ++i) {
;                         const float xv = acc[ai][0][m][n][i], xg = acc[ai][1][m][n][i];
;                         const float uv = m > 0 ? acc[ai][0][m > 0 ? m - 1 : 0][n][i] : 0.f, ug = m > 0 ? acc[ai][1][m > 0 ? m - 1 : 0][n][i] : 0.f;
;                         const float dv = m < 3 ? acc[ai][0][m < 3 ? m + 1 : 3][n][i] : 0.f, dg = m < 3 ? acc[ai][1][m < 3 ? m + 1 : 3][n][i] : 0.f;
;                         const float pv = dpp_ror1(fr == 15 ? uv : xv), pg = dpp_ror1(fr == 15 ? ug : xg);
;                         const float nv = dpp_rol1(fr == 0 ? dv : xv), ng = dpp_rol1(fr == 0 ? dg : xg);
;                         const float yv = wv0[i] * pv + wv1[i] * xv + wv2[i] * nv + bv[i];
;                         const float yg = wg0[i] * pg + wg1[i] * xg + wg2[i] * ng + bg[i];
;                         r[i] = yg * sigmoidf_(yg) * yv;
;                     }
;                     st_bf4(ACT + (size_t)(u.pm * BM + ai * HALF + wr * 64 + m * 16 + fr) * FF + cv, r);
	v_pk_add_f32 v[152:153], v[124:125], v[152:153]
	v_pk_add_f32 v[154:155], v[126:127], v[154:155]
	v_pk_add_f32 v[112:113], v[124:125], v[112:113]
	v_pk_add_f32 v[114:115], v[126:127], v[114:115]
	v_pk_add_f32 v[104:105], v[124:125], v[104:105]
	v_pk_add_f32 v[106:107], v[126:127], v[106:107]
	v_pk_add_f32 v[96:97], v[124:125], v[96:97]
	v_pk_add_f32 v[98:99], v[126:127], v[98:99]
	v_mul_f32_e32 v156, 0xbfb8aa3b, v176
	v_mul_f32_e32 v157, 0xbfb8aa3b, v177
	v_mul_f32_e32 v158, 0xbfb8aa3b, v178
	v_mul_f32_e32 v159, 0xbfb8aa3b, v179
	v_mul_f32_e32 v116, 0xbfb8aa3b, v180
	v_mul_f32_e32 v117, 0xbfb8aa3b, v181
	v_mul_f32_e32 v118, 0xbfb8aa3b, v182
	v_mul_f32_e32 v119, 0xbfb8aa3b, v183
	v_mul_f32_e32 v108, 0xbfb8aa3b, v184
	v_mul_f32_e32 v109, 0xbfb8aa3b, v185
	v_mul_f32_e32 v110, 0xbfb8aa3b, v186
	v_mul_f32_e32 v111, 0xbfb8aa3b, v187
	v_mul_f32_e32 v100, 0xbfb8aa3b, v224
	v_mul_f32_e32 v101, 0xbfb8aa3b, v225
	v_mul_f32_e32 v102, 0xbfb8aa3b, v226
	v_mul_f32_e32 v103, 0xbfb8aa3b, v227
	v_exp_f32_e32 v156, v156
	v_exp_f32_e32 v157, v157
	v_exp_f32_e32 v158, v158
	v_exp_f32_e32 v159, v159
	v_exp_f32_e32 v116, v116
	v_exp_f32_e32 v117, v117
	v_exp_f32_e32 v118, v118
	v_exp_f32_e32 v119, v119
	v_exp_f32_e32 v108, v108
	v_exp_f32_e32 v109, v109
	v_exp_f32_e32 v110, v110
	v_exp_f32_e32 v111, v111
	v_exp_f32_e32 v100, v100
	v_exp_f32_e32 v101, v101
	v_exp_f32_e32 v102, v102
	v_exp_f32_e32 v103, v103
	v_add_f32_e32 v156, 1.0, v156
	v_add_f32_e32 v157, 1.0, v157
	v_add_f32_e32 v158, 1.0, v158
	v_add_f32_e32 v159, 1.0, v159
	v_add_f32_e32 v116, 1.0, v116
	v_add_f32_e32 v117, 1.0, v117
	v_add_f32_e32 v118, 1.0, v118
	v_add_f32_e32 v119, 1.0, v119
	v_add_f32_e32 v108, 1.0, v108
	v_add_f32_e32 v109, 1.0, v109
	v_add_f32_e32 v110, 1.0, v110
	v_add_f32_e32 v111, 1.0, v111
	v_add_f32_e32 v100, 1.0, v100
	v_add_f32_e32 v101, 1.0, v101
	v_add_f32_e32 v102, 1.0, v102
	v_add_f32_e32 v103, 1.0, v103
	v_rcp_f32_e32 v156, v156
	v_rcp_f32_e32 v157, v157
	v_rcp_f32_e32 v158, v158
	v_rcp_f32_e32 v159, v159
	v_rcp_f32_e32 v116, v116
	v_rcp_f32_e32 v117, v117
	v_rcp_f32_e32 v118, v118
	v_rcp_f32_e32 v119, v119
	v_rcp_f32_e32 v108, v108
	v_rcp_f32_e32 v109, v109
	v_rcp_f32_e32 v110, v110
	v_rcp_f32_e32 v111, v111
	v_rcp_f32_e32 v100, v100
	v_rcp_f32_e32 v101, v101
	v_rcp_f32_e32 v102, v102
	v_rcp_f32_e32 v103, v103
	v_pk_mul_f32 v[176:177], v[176:177], v[156:157]
	v_pk_mul_f32 v[178:179], v[178:179], v[158:159]
	v_pk_mul_f32 v[180:181], v[180:181], v[116:117]
	v_pk_mul_f32 v[182:183], v[182:183], v[118:119]
	v_pk_mul_f32 v[184:185], v[184:185], v[108:109]
	v_pk_mul_f32 v[186:187], v[186:187], v[110:111]
	v_pk_mul_f32 v[224:225], v[224:225], v[100:101]
	v_pk_mul_f32 v[226:227], v[226:227], v[102:103]
	v_pk_mul_f32 v[176:177], v[152:153], v[176:177]
	v_pk_mul_f32 v[178:179], v[154:155], v[178:179]
	v_pk_mul_f32 v[180:181], v[112:113], v[180:181]
	v_pk_mul_f32 v[182:183], v[114:115], v[182:183]
	v_pk_mul_f32 v[184:185], v[104:105], v[184:185]
	v_pk_mul_f32 v[186:187], v[106:107], v[186:187]
	v_pk_mul_f32 v[224:225], v[96:97], v[224:225]
	v_pk_mul_f32 v[226:227], v[98:99], v[226:227]
	v_cvt_pk_bf16_f32 v156, v176, v177
	v_cvt_pk_bf16_f32 v157, v178, v179
	v_cvt_pk_bf16_f32 v116, v180, v181
	v_cvt_pk_bf16_f32 v117, v182, v183
	v_cvt_pk_bf16_f32 v108, v184, v185
	v_cvt_pk_bf16_f32 v109, v186, v187
	v_cvt_pk_bf16_f32 v100, v224, v225
	v_cvt_pk_bf16_f32 v101, v226, v227
	global_store_dwordx2 v173, v[156:157], s[0:1]
	v_add_u32_e32 v175, 0x2c00, v173
	global_store_dwordx2 v175, v[116:117], s[0:1]
	v_add_u32_e32 v175, 0x5800, v173
	global_store_dwordx2 v175, v[108:109], s[0:1]
	v_add_u32_e32 v175, 0x8400, v173
	global_store_dwordx2 v175, v[100:101], s[0:1]
	v_mov_b32_dpp v216, v64 row_shr:1 row_mask:0xf bank_mask:0xf bound_ctrl:1
	v_mov_b32_dpp v217, v65 row_shr:1 row_mask:0xf bank_mask:0xf bound_ctrl:1
	v_mov_b32_dpp v218, v66 row_shr:1 row_mask:0xf bank_mask:0xf bound_ctrl:1
	v_mov_b32_dpp v219, v67 row_shr:1 row_mask:0xf bank_mask:0xf bound_ctrl:1
	v_mov_b32_dpp v220, v88 row_shl:1 row_mask:0xf bank_mask:0xf bound_ctrl:1
	v_mov_b32_dpp v221, v89 row_shl:1 row_mask:0xf bank_mask:0xf bound_ctrl:1
	v_mov_b32_dpp v222, v90 row_shl:1 row_mask:0xf bank_mask:0xf bound_ctrl:1
	v_mov_b32_dpp v223, v91 row_shl:1 row_mask:0xf bank_mask:0xf bound_ctrl:1
	v_pk_mul_f32 v[176:177], v[88:89], v[234:235]
	v_pk_mul_f32 v[178:179], v[90:91], v[236:237]
	v_pk_mul_f32 v[180:181], v[80:81], v[234:235]
	v_pk_mul_f32 v[182:183], v[82:83], v[236:237]
	v_pk_mul_f32 v[184:185], v[72:73], v[234:235]
	v_pk_mul_f32 v[186:187], v[74:75], v[236:237]
	v_pk_mul_f32 v[224:225], v[64:65], v[234:235]
	v_pk_mul_f32 v[226:227], v[66:67], v[236:237]
	v_pk_fma_f32 v[176:177], v[230:231], v[216:217], v[176:177]
	v_pk_fma_f32 v[178:179], v[232:233], v[218:219], v[178:179]
	v_pk_fma_f32 v[180:181], v[230:231], v[88:89], v[180:181]
	v_pk_fma_f32 v[182:183], v[232:233], v[90:91], v[182:183]
	v_pk_fma_f32 v[184:185], v[230:231], v[80:81], v[184:185]
	v_pk_fma_f32 v[186:187], v[232:233], v[82:83], v[186:187]
	v_pk_fma_f32 v[224:225], v[230:231], v[72:73], v[224:225]
	v_pk_fma_f32 v[226:227], v[232:233], v[74:75], v[226:227]
	v_pk_fma_f32 v[176:177], v[238:239], v[80:81], v[176:177]
	v_pk_fma_f32 v[178:179], v[240:241], v[82:83], v[178:179]
	v_pk_fma_f32 v[180:181], v[238:239], v[72:73], v[180:181]
	v_pk_fma_f32 v[182:183], v[240:241], v[74:75], v[182:183]
	v_pk_fma_f32 v[184:185], v[238:239], v[64:65], v[184:185]
	v_pk_fma_f32 v[186:187], v[240:241], v[66:67], v[186:187]
	v_pk_fma_f32 v[224:225], v[238:239], v[220:221], v[224:225]
	v_pk_fma_f32 v[226:227], v[240:241], v[222:223], v[226:227]
	v_pk_add_f32 v[176:177], v[242:243], v[176:177]
; __device__ __forceinline__ void st_bf4(bf16_t* p, f32x4 v) { u32x2 w; w.x = pk2(v[0], v[1]); w.y = pk2(v[2], v[3]); *(u32x2*)p = w; }
; __device__ __forceinline__ float sigmoidf_(float x) { return __builtin_amdgcn_rcpf(1.f + __expf(-x)); }
; __device__ __forceinline__ float dpp_ror1(float v) { return __int_as_float(__builtin_amdgcn_update_dpp(0, __float_as_int(v), 0x121, 0xf, 0xf, false)); }
; __device__ __forceinline__ float dpp_rol1(float v) { return __int_as_float(__builtin_amdgcn_update_dpp(0, __float_as_int(v), 0x12F, 0xf, 0xf, false)); }
;     __device__ __forceinline__ void tile(const f32x4 (&acc)[2][2][4][2], const Unit& u, int wr, int wc, int fr, int fq) const {
;     ...
;                     for (int i = 0; i < 4; ++i) {
;                         const float xv = acc[ai][0][m][n][i], xg = acc[ai][1][m][n][i];
;                         const float uv = m > 0 ? acc[ai][0][m > 0 ? m - 1 : 0][n][i] : 0.f, ug = m > 0 ? acc[ai][1][m > 0 ? m - 1 : 0][n][i] : 0.f;
;                         const float dv = m < 3 ? acc[ai][0][m < 3 ? m + 1 : 3][n][i] : 0.f, dg = m < 3 ? acc[ai][1][m < 3 ? m + 1 : 3][n][i] : 0.f;
;                         const float pv = dpp_ror1(fr == 15 ? uv : xv), pg = dpp_ror1(fr == 15 ? ug : xg);
;                         const float nv = dpp_rol1(fr == 0 ? dv : xv), ng = dpp_rol1(fr == 0 ? dg : xg);
;                         const float yv = wv0[i] * pv + wv1[i] * xv + wv2[i] * nv + bv[i];
;                         const float yg = wg0[i] * pg + wg1[i] * xg + wg2[i] * ng + bg[i];
;                         r[i] = yg * sigmoidf_(yg) * yv;
;                     }
;                     st_bf4(ACT + (size_t)(u.pm * BM + ai * HALF + wr * 64 + m * 16 + fr) * FF + cv, r);
	v_pk_add_f32 v[178:179], v[244:245], v[178:179]
	v_pk_add_f32 v[180:181], v[242:243], v[180:181]
	v_pk_add_f32 v[182:183], v[244:245], v[182:183]
	v_pk_add_f32 v[184:185], v[242:243], v[184:185]
	v_pk_add_f32 v[186:187], v[244:245], v[186:187]
	v_pk_add_f32 v[224:225], v[242:243], v[224:225]
	v_pk_add_f32 v[226:227], v[244:245], v[226:227]
	v_mov_b32_dpp v216, v68 row_shr:1 row_mask:0xf bank_mask:0xf bound_ctrl:1
	v_mov_b32_dpp v217, v69 row_shr:1 row_mask:0xf bank_mask:0xf bound_ctrl:1
	v_mov_b32_dpp v218, v70 row_shr:1 row_mask:0xf bank_mask:0xf bound_ctrl:1
	v_mov_b32_dpp v219, v71 row_shr:1 row_mask:0xf bank_mask:0xf bound_ctrl:1
	v_mov_b32_dpp v220, v92 row_shl:1 row_mask:0xf bank_mask:0xf bound_ctrl:1
	v_mov_b32_dpp v221, v93 row_shl:1 row_mask:0xf bank_mask:0xf bound_ctrl:1
	v_mov_b32_dpp v222, v94 row_shl:1 row_mask:0xf bank_mask:0xf bound_ctrl:1
	v_mov_b32_dpp v223, v95 row_shl:1 row_mask:0xf bank_mask:0xf bound_ctrl:1
	v_pk_mul_f32 v[88:89], v[92:93], v[250:251]
	v_pk_mul_f32 v[90:91], v[94:95], v[252:253]
	v_pk_mul_f32 v[80:81], v[84:85], v[250:251]
	v_pk_mul_f32 v[82:83], v[86:87], v[252:253]
	v_pk_mul_f32 v[72:73], v[76:77], v[250:251]
	v_pk_mul_f32 v[74:75], v[78:79], v[252:253]
	v_pk_mul_f32 v[64:65], v[68:69], v[250:251]
	v_pk_mul_f32 v[66:67], v[70:71], v[252:253]
	v_pk_fma_f32 v[88:89], v[246:247], v[216:217], v[88:89]
	v_pk_fma_f32 v[90:91], v[248:249], v[218:219], v[90:91]
	v_pk_fma_f32 v[80:81], v[246:247], v[92:93], v[80:81]
	v_pk_fma_f32 v[82:83], v[248:249], v[94:95], v[82:83]
	v_pk_fma_f32 v[72:73], v[246:247], v[84:85], v[72:73]
	v_pk_fma_f32 v[74:75], v[248:249], v[86:87], v[74:75]
	v_pk_fma_f32 v[64:65], v[246:247], v[76:77], v[64:65]
	v_pk_fma_f32 v[66:67], v[248:249], v[78:79], v[66:67]
	v_pk_fma_f32 v[88:89], v[120:121], v[84:85], v[88:89]
	v_pk_fma_f32 v[90:91], v[122:123], v[86:87], v[90:91]
	v_pk_fma_f32 v[80:81], v[120:121], v[76:77], v[80:81]
	v_pk_fma_f32 v[82:83], v[122:123], v[78:79], v[82:83]
	v_pk_fma_f32 v[72:73], v[120:121], v[68:69], v[72:73]
	v_pk_fma_f32 v[74:75], v[122:123], v[70:71], v[74:75]
	v_pk_fma_f32 v[64:65], v[120:121], v[220:221], v[64:65]
	v_pk_fma_f32 v[66:67], v[122:123], v[222:223], v[66:67]
	v_pk_add_f32 v[88:89], v[124:125], v[88:89]
	v_pk_add_f32 v[90:91], v[126:127], v[90:91]
	v_pk_add_f32 v[80:81], v[124:125], v[80:81]
	v_pk_add_f32 v[82:83], v[126:127], v[82:83]
	v_pk_add_f32 v[72:73], v[124:125], v[72:73]
	v_pk_add_f32 v[74:75], v[126:127], v[74:75]
	v_pk_add_f32 v[64:65], v[124:125], v[64:65]
	v_pk_add_f32 v[66:67], v[126:127], v[66:67]
	v_mul_f32_e32 v92, 0xbfb8aa3b, v176
	v_mul_f32_e32 v93, 0xbfb8aa3b, v177
	v_mul_f32_e32 v94, 0xbfb8aa3b, v178
	v_mul_f32_e32 v95, 0xbfb8aa3b, v179
	v_mul_f32_e32 v84, 0xbfb8aa3b, v180
	v_mul_f32_e32 v85, 0xbfb8aa3b, v181
	v_mul_f32_e32 v86, 0xbfb8aa3b, v182
	v_mul_f32_e32 v87, 0xbfb8aa3b, v183
	v_mul_f32_e32 v76, 0xbfb8aa3b, v184
	v_mul_f32_e32 v77, 0xbfb8aa3b, v185
	v_mul_f32_e32 v78, 0xbfb8aa3b, v186
	v_mul_f32_e32 v79, 0xbfb8aa3b, v187
	v_mul_f32_e32 v68, 0xbfb8aa3b, v224
	v_mul_f32_e32 v69, 0xbfb8aa3b, v225
	v_mul_f32_e32 v70, 0xbfb8aa3b, v226
	v_mul_f32_e32 v71, 0xbfb8aa3b, v227
	v_exp_f32_e32 v92, v92
	v_exp_f32_e32 v93, v93
	v_exp_f32_e32 v94, v94
	v_exp_f32_e32 v95, v95
	v_exp_f32_e32 v84, v84
	v_exp_f32_e32 v85, v85
	v_exp_f32_e32 v86, v86
	v_exp_f32_e32 v87, v87
	v_exp_f32_e32 v76, v76
	v_exp_f32_e32 v77, v77
	v_exp_f32_e32 v78, v78
	v_exp_f32_e32 v79, v79
	v_exp_f32_e32 v68, v68
	v_exp_f32_e32 v69, v69
	v_exp_f32_e32 v70, v70
	v_exp_f32_e32 v71, v71
	v_add_f32_e32 v92, 1.0, v92
	v_add_f32_e32 v93, 1.0, v93
	v_add_f32_e32 v94, 1.0, v94
	v_add_f32_e32 v95, 1.0, v95
	v_add_f32_e32 v84, 1.0, v84
	v_add_f32_e32 v85, 1.0, v85
	v_add_f32_e32 v86, 1.0, v86
	v_add_f32_e32 v87, 1.0, v87
	v_add_f32_e32 v76, 1.0, v76
	v_add_f32_e32 v77, 1.0, v77
	v_add_f32_e32 v78, 1.0, v78
	v_add_f32_e32 v79, 1.0, v79
	v_add_f32_e32 v68, 1.0, v68
	v_add_f32_e32 v69, 1.0, v69
	v_add_f32_e32 v70, 1.0, v70
	v_add_f32_e32 v71, 1.0, v71
	v_rcp_f32_e32 v92, v92
	v_rcp_f32_e32 v93, v93
	v_rcp_f32_e32 v94, v94
	v_rcp_f32_e32 v95, v95
	v_rcp_f32_e32 v84, v84
	v_rcp_f32_e32 v85, v85
	v_rcp_f32_e32 v86, v86
	v_rcp_f32_e32 v87, v87
	v_rcp_f32_e32 v76, v76
	v_rcp_f32_e32 v77, v77
	v_rcp_f32_e32 v78, v78
	v_rcp_f32_e32 v79, v79
	v_rcp_f32_e32 v68, v68
	v_rcp_f32_e32 v69, v69
	v_rcp_f32_e32 v70, v70
	v_rcp_f32_e32 v71, v71
	v_pk_mul_f32 v[176:177], v[176:177], v[92:93]
	v_pk_mul_f32 v[178:179], v[178:179], v[94:95]
	v_pk_mul_f32 v[180:181], v[180:181], v[84:85]
	v_pk_mul_f32 v[182:183], v[182:183], v[86:87]
	v_pk_mul_f32 v[184:185], v[184:185], v[76:77]
	v_pk_mul_f32 v[186:187], v[186:187], v[78:79]
	v_pk_mul_f32 v[224:225], v[224:225], v[68:69]
	v_pk_mul_f32 v[226:227], v[226:227], v[70:71]
	v_pk_mul_f32 v[176:177], v[88:89], v[176:177]
	v_pk_mul_f32 v[178:179], v[90:91], v[178:179]
	v_pk_mul_f32 v[180:181], v[80:81], v[180:181]
	v_pk_mul_f32 v[182:183], v[82:83], v[182:183]
	v_pk_mul_f32 v[184:185], v[72:73], v[184:185]
	v_pk_mul_f32 v[186:187], v[74:75], v[186:187]
	v_pk_mul_f32 v[224:225], v[64:65], v[224:225]
	v_pk_mul_f32 v[226:227], v[66:67], v[226:227]
	v_cvt_pk_bf16_f32 v92, v176, v177
	v_cvt_pk_bf16_f32 v93, v178, v179
	v_cvt_pk_bf16_f32 v84, v180, v181
	v_cvt_pk_bf16_f32 v85, v182, v183
	v_cvt_pk_bf16_f32 v76, v184, v185
	v_cvt_pk_bf16_f32 v77, v186, v187
	v_cvt_pk_bf16_f32 v68, v224, v225
	v_cvt_pk_bf16_f32 v69, v226, v227
	global_store_dwordx2 v174, v[92:93], s[0:1]
	v_add_u32_e32 v175, 0x2c00, v174
	global_store_dwordx2 v175, v[84:85], s[0:1]
	v_add_u32_e32 v175, 0x5800, v174
	global_store_dwordx2 v175, v[76:77], s[0:1]
	v_add_u32_e32 v175, 0x8400, v174
	global_store_dwordx2 v175, v[68:69], s[0:1]
	s_waitcnt vmcnt(12)
; __device__ __forceinline__ float sigmoidf_(float x) { return __builtin_amdgcn_rcpf(1.f + __expf(-x)); }
; __device__ __forceinline__ float dpp_ror1(float v) { return __int_as_float(__builtin_amdgcn_update_dpp(0, __float_as_int(v), 0x121, 0xf, 0xf, false)); }
; __device__ __forceinline__ float dpp_rol1(float v) { return __int_as_float(__builtin_amdgcn_update_dpp(0, __float_as_int(v), 0x12F, 0xf, 0xf, false)); }
;     __device__ __forceinline__ void tile(const f32x4 (&acc)[2][2][4][2], const Unit& u, int wr, int wc, int fr, int fq) const {
;     ...
;                     for (int i = 0; i < 4; ++i) {
;                         const float xv = acc[ai][0][m][n][i], xg = acc[ai][1][m][n][i];
;                         const float uv = m > 0 ? acc[ai][0][m > 0 ? m - 1 : 0][n][i] : 0.f, ug = m > 0 ? acc[ai][1][m > 0 ? m - 1 : 0][n][i] : 0.f;
;                         const float dv = m < 3 ? acc[ai][0][m < 3 ? m + 1 : 3][n][i] : 0.f, dg = m < 3 ? acc[ai][1][m < 3 ? m + 1 : 3][n][i] : 0.f;
;                         const float pv = dpp_ror1(fr == 15 ? uv : xv), pg = dpp_ror1(fr == 15 ? ug : xg);
;                         const float nv = dpp_rol1(fr == 0 ? dv : xv), ng = dpp_rol1(fr == 0 ? dg : xg);
;                         const float yv = wv0[i] * pv + wv1[i] * xv + wv2[i] * nv + bv[i];
;                         const float yg = wg0[i] * pg + wg1[i] * xg + wg2[i] * ng + bg[i];
;                         r[i] = yg * sigmoidf_(yg) * yv;
	v_mov_b32_dpp v216, v32 row_shr:1 row_mask:0xf bank_mask:0xf bound_ctrl:1
	v_mov_b32_dpp v217, v33 row_shr:1 row_mask:0xf bank_mask:0xf bound_ctrl:1
	v_mov_b32_dpp v218, v34 row_shr:1 row_mask:0xf bank_mask:0xf bound_ctrl:1
	v_mov_b32_dpp v219, v35 row_shr:1 row_mask:0xf bank_mask:0xf bound_ctrl:1
	v_mov_b32_dpp v220, v56 row_shl:1 row_mask:0xf bank_mask:0xf bound_ctrl:1
	v_mov_b32_dpp v221, v57 row_shl:1 row_mask:0xf bank_mask:0xf bound_ctrl:1
	v_mov_b32_dpp v222, v58 row_shl:1 row_mask:0xf bank_mask:0xf bound_ctrl:1
	v_mov_b32_dpp v223, v59 row_shl:1 row_mask:0xf bank_mask:0xf bound_ctrl:1
	v_pk_mul_f32 v[176:177], v[56:57], v[132:133]
	v_pk_mul_f32 v[178:179], v[58:59], v[134:135]
	v_pk_mul_f32 v[180:181], v[48:49], v[132:133]
	v_pk_mul_f32 v[182:183], v[50:51], v[134:135]
	v_pk_mul_f32 v[184:185], v[40:41], v[132:133]
	v_pk_mul_f32 v[186:187], v[42:43], v[134:135]
	v_pk_mul_f32 v[224:225], v[32:33], v[132:133]
	v_pk_mul_f32 v[226:227], v[34:35], v[134:135]
	v_pk_fma_f32 v[176:177], v[128:129], v[216:217], v[176:177]
	v_pk_fma_f32 v[178:179], v[130:131], v[218:219], v[178:179]
	v_pk_fma_f32 v[180:181], v[128:129], v[56:57], v[180:181]
	v_pk_fma_f32 v[182:183], v[130:131], v[58:59], v[182:183]
	v_pk_fma_f32 v[184:185], v[128:129], v[48:49], v[184:185]
	v_pk_fma_f32 v[186:187], v[130:131], v[50:51], v[186:187]
	v_pk_fma_f32 v[224:225], v[128:129], v[40:41], v[224:225]
	v_pk_fma_f32 v[226:227], v[130:131], v[42:43], v[226:227]
	v_pk_fma_f32 v[176:177], v[136:137], v[48:49], v[176:177]
	v_pk_fma_f32 v[178:179], v[138:139], v[50:51], v[178:179]
	v_pk_fma_f32 v[180:181], v[136:137], v[40:41], v[180:181]
	v_pk_fma_f32 v[182:183], v[138:139], v[42:43], v[182:183]
	v_pk_fma_f32 v[184:185], v[136:137], v[32:33], v[184:185]
	v_pk_fma_f32 v[186:187], v[138:139], v[34:35], v[186:187]
	v_pk_fma_f32 v[224:225], v[136:137], v[220:221], v[224:225]
	v_pk_fma_f32 v[226:227], v[138:139], v[222:223], v[226:227]
	v_pk_add_f32 v[176:177], v[140:141], v[176:177]
	v_pk_add_f32 v[178:179], v[142:143], v[178:179]
	v_pk_add_f32 v[180:181], v[140:141], v[180:181]
	v_pk_add_f32 v[182:183], v[142:143], v[182:183]
	v_pk_add_f32 v[184:185], v[140:141], v[184:185]
	v_pk_add_f32 v[186:187], v[142:143], v[186:187]
	v_pk_add_f32 v[224:225], v[140:141], v[224:225]
	v_pk_add_f32 v[226:227], v[142:143], v[226:227]
	s_waitcnt vmcnt(8)
	v_mov_b32_dpp v216, v36 row_shr:1 row_mask:0xf bank_mask:0xf bound_ctrl:1
	v_mov_b32_dpp v217, v37 row_shr:1 row_mask:0xf bank_mask:0xf bound_ctrl:1
	v_mov_b32_dpp v218, v38 row_shr:1 row_mask:0xf bank_mask:0xf bound_ctrl:1
	v_mov_b32_dpp v219, v39 row_shr:1 row_mask:0xf bank_mask:0xf bound_ctrl:1
	v_mov_b32_dpp v220, v60 row_shl:1 row_mask:0xf bank_mask:0xf bound_ctrl:1
	v_mov_b32_dpp v221, v61 row_shl:1 row_mask:0xf bank_mask:0xf bound_ctrl:1
	v_mov_b32_dpp v222, v62 row_shl:1 row_mask:0xf bank_mask:0xf bound_ctrl:1
	v_mov_b32_dpp v223, v63 row_shl:1 row_mask:0xf bank_mask:0xf bound_ctrl:1
	v_pk_mul_f32 v[56:57], v[60:61], v[148:149]
	v_pk_mul_f32 v[58:59], v[62:63], v[150:151]
	v_pk_mul_f32 v[48:49], v[52:53], v[148:149]
	v_pk_mul_f32 v[50:51], v[54:55], v[150:151]
	v_pk_mul_f32 v[40:41], v[44:45], v[148:149]
	v_pk_mul_f32 v[42:43], v[46:47], v[150:151]
	v_pk_mul_f32 v[32:33], v[36:37], v[148:149]
	v_pk_mul_f32 v[34:35], v[38:39], v[150:151]
	v_pk_fma_f32 v[56:57], v[144:145], v[216:217], v[56:57]
	v_pk_fma_f32 v[58:59], v[146:147], v[218:219], v[58:59]
	v_pk_fma_f32 v[48:49], v[144:145], v[60:61], v[48:49]
	v_pk_fma_f32 v[50:51], v[146:147], v[62:63], v[50:51]
	v_pk_fma_f32 v[40:41], v[144:145], v[52:53], v[40:41]
	v_pk_fma_f32 v[42:43], v[146:147], v[54:55], v[42:43]
	v_pk_fma_f32 v[32:33], v[144:145], v[44:45], v[32:33]
	v_pk_fma_f32 v[34:35], v[146:147], v[46:47], v[34:35]
	v_pk_fma_f32 v[56:57], v[208:209], v[52:53], v[56:57]
	v_pk_fma_f32 v[58:59], v[210:211], v[54:55], v[58:59]
	v_pk_fma_f32 v[48:49], v[208:209], v[44:45], v[48:49]
	v_pk_fma_f32 v[50:51], v[210:211], v[46:47], v[50:51]
	v_pk_fma_f32 v[40:41], v[208:209], v[36:37], v[40:41]
	v_pk_fma_f32 v[42:43], v[210:211], v[38:39], v[42:43]
	v_pk_fma_f32 v[32:33], v[208:209], v[220:221], v[32:33]
	v_pk_fma_f32 v[34:35], v[210:211], v[222:223], v[34:35]
	v_pk_add_f32 v[56:57], v[212:213], v[56:57]
	v_pk_add_f32 v[58:59], v[214:215], v[58:59]
	v_pk_add_f32 v[48:49], v[212:213], v[48:49]
	v_pk_add_f32 v[50:51], v[214:215], v[50:51]
	v_pk_add_f32 v[40:41], v[212:213], v[40:41]
	v_pk_add_f32 v[42:43], v[214:215], v[42:43]
	v_pk_add_f32 v[32:33], v[212:213], v[32:33]
	v_pk_add_f32 v[34:35], v[214:215], v[34:35]
	v_mul_f32_e32 v60, 0xbfb8aa3b, v176
	v_mul_f32_e32 v61, 0xbfb8aa3b, v177
	v_mul_f32_e32 v62, 0xbfb8aa3b, v178
	v_mul_f32_e32 v63, 0xbfb8aa3b, v179
	v_mul_f32_e32 v52, 0xbfb8aa3b, v180
	v_mul_f32_e32 v53, 0xbfb8aa3b, v181
	v_mul_f32_e32 v54, 0xbfb8aa3b, v182
	v_mul_f32_e32 v55, 0xbfb8aa3b, v183
	v_mul_f32_e32 v44, 0xbfb8aa3b, v184
	v_mul_f32_e32 v45, 0xbfb8aa3b, v185
	v_mul_f32_e32 v46, 0xbfb8aa3b, v186
	v_mul_f32_e32 v47, 0xbfb8aa3b, v187
	v_mul_f32_e32 v36, 0xbfb8aa3b, v224
	v_mul_f32_e32 v37, 0xbfb8aa3b, v225
	v_mul_f32_e32 v38, 0xbfb8aa3b, v226
	v_mul_f32_e32 v39, 0xbfb8aa3b, v227
	v_exp_f32_e32 v60, v60
	v_exp_f32_e32 v61, v61
	v_exp_f32_e32 v62, v62
	v_exp_f32_e32 v63, v63
	v_exp_f32_e32 v52, v52
	v_exp_f32_e32 v53, v53
	v_exp_f32_e32 v54, v54
	v_exp_f32_e32 v55, v55
	v_exp_f32_e32 v44, v44
	v_exp_f32_e32 v45, v45
	v_exp_f32_e32 v46, v46
	v_exp_f32_e32 v47, v47
	v_exp_f32_e32 v36, v36
	v_exp_f32_e32 v37, v37
	v_exp_f32_e32 v38, v38
	v_exp_f32_e32 v39, v39
	v_add_f32_e32 v60, 1.0, v60
	v_add_f32_e32 v61, 1.0, v61
	v_add_f32_e32 v62, 1.0, v62
	v_add_f32_e32 v63, 1.0, v63
; __device__ __forceinline__ void st_bf4(bf16_t* p, f32x4 v) { u32x2 w; w.x = pk2(v[0], v[1]); w.y = pk2(v[2], v[3]); *(u32x2*)p = w; }
; __device__ __forceinline__ float sigmoidf_(float x) { return __builtin_amdgcn_rcpf(1.f + __expf(-x)); }
; __device__ __forceinline__ float dpp_ror1(float v) { return __int_as_float(__builtin_amdgcn_update_dpp(0, __float_as_int(v), 0x121, 0xf, 0xf, false)); }
; __device__ __forceinline__ float dpp_rol1(float v) { return __int_as_float(__builtin_amdgcn_update_dpp(0, __float_as_int(v), 0x12F, 0xf, 0xf, false)); }
;     __device__ __forceinline__ void tile(const f32x4 (&acc)[2][2][4][2], const Unit& u, int wr, int wc, int fr, int fq) const {
;     ...
;                     for (int i = 0; i < 4; ++i) {
;                         const float xv = acc[ai][0][m][n][i], xg = acc[ai][1][m][n][i];
;                         const float uv = m > 0 ? acc[ai][0][m > 0 ? m - 1 : 0][n][i] : 0.f, ug = m > 0 ? acc[ai][1][m > 0 ? m - 1 : 0][n][i] : 0.f;
;                         const float dv = m < 3 ? acc[ai][0][m < 3 ? m + 1 : 3][n][i] : 0.f, dg = m < 3 ? acc[ai][1][m < 3 ? m + 1 : 3][n][i] : 0.f;
;                         const float pv = dpp_ror1(fr == 15 ? uv : xv), pg = dpp_ror1(fr == 15 ? ug : xg);
;                         const float nv = dpp_rol1(fr == 0 ? dv : xv), ng = dpp_rol1(fr == 0 ? dg : xg);
;                         const float yv = wv0[i] * pv + wv1[i] * xv + wv2[i] * nv + bv[i];
;                         const float yg = wg0[i] * pg + wg1[i] * xg + wg2[i] * ng + bg[i];
;                         r[i] = yg * sigmoidf_(yg) * yv;
;                     }
;                     st_bf4(ACT + (size_t)(u.pm * BM + ai * HALF + wr * 64 + m * 16 + fr) * FF + cv, r);
	v_add_f32_e32 v52, 1.0, v52
	v_add_f32_e32 v53, 1.0, v53
	v_add_f32_e32 v54, 1.0, v54
	v_add_f32_e32 v55, 1.0, v55
	v_add_f32_e32 v44, 1.0, v44
	v_add_f32_e32 v45, 1.0, v45
	v_add_f32_e32 v46, 1.0, v46
	v_add_f32_e32 v47, 1.0, v47
	v_add_f32_e32 v36, 1.0, v36
	v_add_f32_e32 v37, 1.0, v37
	v_add_f32_e32 v38, 1.0, v38
	v_add_f32_e32 v39, 1.0, v39
	v_rcp_f32_e32 v60, v60
	v_rcp_f32_e32 v61, v61
	v_rcp_f32_e32 v62, v62
	v_rcp_f32_e32 v63, v63
	v_rcp_f32_e32 v52, v52
	v_rcp_f32_e32 v53, v53
	v_rcp_f32_e32 v54, v54
	v_rcp_f32_e32 v55, v55
	v_rcp_f32_e32 v44, v44
	v_rcp_f32_e32 v45, v45
	v_rcp_f32_e32 v46, v46
	v_rcp_f32_e32 v47, v47
	v_rcp_f32_e32 v36, v36
	v_rcp_f32_e32 v37, v37
	v_rcp_f32_e32 v38, v38
	v_rcp_f32_e32 v39, v39
	v_pk_mul_f32 v[176:177], v[176:177], v[60:61]
	v_pk_mul_f32 v[178:179], v[178:179], v[62:63]
	v_pk_mul_f32 v[180:181], v[180:181], v[52:53]
	v_pk_mul_f32 v[182:183], v[182:183], v[54:55]
	v_pk_mul_f32 v[184:185], v[184:185], v[44:45]
	v_pk_mul_f32 v[186:187], v[186:187], v[46:47]
	v_pk_mul_f32 v[224:225], v[224:225], v[36:37]
	v_pk_mul_f32 v[226:227], v[226:227], v[38:39]
	v_pk_mul_f32 v[176:177], v[56:57], v[176:177]
	v_pk_mul_f32 v[178:179], v[58:59], v[178:179]
	v_pk_mul_f32 v[180:181], v[48:49], v[180:181]
	v_pk_mul_f32 v[182:183], v[50:51], v[182:183]
	v_pk_mul_f32 v[184:185], v[40:41], v[184:185]
	v_pk_mul_f32 v[186:187], v[42:43], v[186:187]
	v_pk_mul_f32 v[224:225], v[32:33], v[224:225]
	v_pk_mul_f32 v[226:227], v[34:35], v[226:227]
	v_cvt_pk_bf16_f32 v60, v176, v177
	v_cvt_pk_bf16_f32 v61, v178, v179
	v_cvt_pk_bf16_f32 v52, v180, v181
	v_cvt_pk_bf16_f32 v53, v182, v183
	v_cvt_pk_bf16_f32 v44, v184, v185
	v_cvt_pk_bf16_f32 v45, v186, v187
	v_cvt_pk_bf16_f32 v36, v224, v225
	v_cvt_pk_bf16_f32 v37, v226, v227
	global_store_dwordx2 v173, v[60:61], s[0:1] offset:32
	v_add_u32_e32 v175, 0x2c00, v173
	global_store_dwordx2 v175, v[52:53], s[0:1] offset:32
	v_add_u32_e32 v175, 0x5800, v173
	global_store_dwordx2 v175, v[44:45], s[0:1] offset:32
	v_add_u32_e32 v175, 0x8400, v173
	global_store_dwordx2 v175, v[36:37], s[0:1] offset:32
	v_mov_b32_dpp v216, v0 row_shr:1 row_mask:0xf bank_mask:0xf bound_ctrl:1
	v_mov_b32_dpp v217, v1 row_shr:1 row_mask:0xf bank_mask:0xf bound_ctrl:1
	v_mov_b32_dpp v218, v2 row_shr:1 row_mask:0xf bank_mask:0xf bound_ctrl:1
	v_mov_b32_dpp v219, v3 row_shr:1 row_mask:0xf bank_mask:0xf bound_ctrl:1
	v_mov_b32_dpp v220, v24 row_shl:1 row_mask:0xf bank_mask:0xf bound_ctrl:1
	v_mov_b32_dpp v221, v25 row_shl:1 row_mask:0xf bank_mask:0xf bound_ctrl:1
	v_mov_b32_dpp v222, v26 row_shl:1 row_mask:0xf bank_mask:0xf bound_ctrl:1
	v_mov_b32_dpp v223, v27 row_shl:1 row_mask:0xf bank_mask:0xf bound_ctrl:1
	v_pk_mul_f32 v[176:177], v[24:25], v[132:133]
	v_pk_mul_f32 v[178:179], v[26:27], v[134:135]
	v_pk_mul_f32 v[180:181], v[16:17], v[132:133]
	v_pk_mul_f32 v[182:183], v[18:19], v[134:135]
	v_pk_mul_f32 v[184:185], v[8:9], v[132:133]
	v_pk_mul_f32 v[186:187], v[10:11], v[134:135]
	v_pk_mul_f32 v[224:225], v[0:1], v[132:133]
	v_pk_mul_f32 v[226:227], v[2:3], v[134:135]
	v_pk_fma_f32 v[176:177], v[128:129], v[216:217], v[176:177]
	v_pk_fma_f32 v[178:179], v[130:131], v[218:219], v[178:179]
	v_pk_fma_f32 v[180:181], v[128:129], v[24:25], v[180:181]
	v_pk_fma_f32 v[182:183], v[130:131], v[26:27], v[182:183]
	v_pk_fma_f32 v[184:185], v[128:129], v[16:17], v[184:185]
	v_pk_fma_f32 v[186:187], v[130:131], v[18:19], v[186:187]
	v_pk_fma_f32 v[224:225], v[128:129], v[8:9], v[224:225]
	v_pk_fma_f32 v[226:227], v[130:131], v[10:11], v[226:227]
	v_pk_fma_f32 v[176:177], v[136:137], v[16:17], v[176:177]
	v_pk_fma_f32 v[178:179], v[138:139], v[18:19], v[178:179]
	v_pk_fma_f32 v[180:181], v[136:137], v[8:9], v[180:181]
	v_pk_fma_f32 v[182:183], v[138:139], v[10:11], v[182:183]
	v_pk_fma_f32 v[184:185], v[136:137], v[0:1], v[184:185]
	v_pk_fma_f32 v[186:187], v[138:139], v[2:3], v[186:187]
	v_pk_fma_f32 v[224:225], v[136:137], v[220:221], v[224:225]
	v_pk_fma_f32 v[226:227], v[138:139], v[222:223], v[226:227]
	v_pk_add_f32 v[176:177], v[140:141], v[176:177]
	v_pk_add_f32 v[178:179], v[142:143], v[178:179]
	v_pk_add_f32 v[180:181], v[140:141], v[180:181]
	v_pk_add_f32 v[182:183], v[142:143], v[182:183]
	v_pk_add_f32 v[184:185], v[140:141], v[184:185]
	v_pk_add_f32 v[186:187], v[142:143], v[186:187]
	v_pk_add_f32 v[224:225], v[140:141], v[224:225]
	v_pk_add_f32 v[226:227], v[142:143], v[226:227]
	v_mov_b32_dpp v216, v4 row_shr:1 row_mask:0xf bank_mask:0xf bound_ctrl:1
	v_mov_b32_dpp v217, v5 row_shr:1 row_mask:0xf bank_mask:0xf bound_ctrl:1
	v_mov_b32_dpp v218, v6 row_shr:1 row_mask:0xf bank_mask:0xf bound_ctrl:1
	v_mov_b32_dpp v219, v7 row_shr:1 row_mask:0xf bank_mask:0xf bound_ctrl:1
	v_mov_b32_dpp v220, v28 row_shl:1 row_mask:0xf bank_mask:0xf bound_ctrl:1
	v_mov_b32_dpp v221, v29 row_shl:1 row_mask:0xf bank_mask:0xf bound_ctrl:1
	v_mov_b32_dpp v222, v30 row_shl:1 row_mask:0xf bank_mask:0xf bound_ctrl:1
	v_mov_b32_dpp v223, v31 row_shl:1 row_mask:0xf bank_mask:0xf bound_ctrl:1
	v_pk_mul_f32 v[24:25], v[28:29], v[148:149]
	v_pk_mul_f32 v[26:27], v[30:31], v[150:151]
	v_pk_mul_f32 v[16:17], v[20:21], v[148:149]
; __device__ __forceinline__ void st_bf4(bf16_t* p, f32x4 v) { u32x2 w; w.x = pk2(v[0], v[1]); w.y = pk2(v[2], v[3]); *(u32x2*)p = w; }
; __device__ __forceinline__ float sigmoidf_(float x) { return __builtin_amdgcn_rcpf(1.f + __expf(-x)); }
; __device__ __forceinline__ float dpp_ror1(float v) { return __int_as_float(__builtin_amdgcn_update_dpp(0, __float_as_int(v), 0x121, 0xf, 0xf, false)); }
; __device__ __forceinline__ float dpp_rol1(float v) { return __int_as_float(__builtin_amdgcn_update_dpp(0, __float_as_int(v), 0x12F, 0xf, 0xf, false)); }
;     __device__ __forceinline__ void tile(const f32x4 (&acc)[2][2][4][2], const Unit& u, int wr, int wc, int fr, int fq) const {
;     ...
;             const int cv = 128 * u.pn + 32 * wc + 16 * n + 4 * fq, cg = FF + cv;
;             const f32x4 wv0 = *(const f32x4*)(cw + cv), wv1 = *(const f32x4*)(cw + F2 + cv), wv2 = *(const f32x4*)(cw + 2 * F2 + cv), bv = *(const f32x4*)(cb + cv);
;             const f32x4 wg0 = *(const f32x4*)(cw + cg), wg1 = *(const f32x4*)(cw + F2 + cg), wg2 = *(const f32x4*)(cw + 2 * F2 + cg), bg = *(const f32x4*)(cb + cg);
;     ...
;                     for (int i = 0; i < 4; ++i) {
;                         const float xv = acc[ai][0][m][n][i], xg = acc[ai][1][m][n][i];
;                         const float uv = m > 0 ? acc[ai][0][m > 0 ? m - 1 : 0][n][i] : 0.f, ug = m > 0 ? acc[ai][1][m > 0 ? m - 1 : 0][n][i] : 0.f;
;                         const float dv = m < 3 ? acc[ai][0][m < 3 ? m + 1 : 3][n][i] : 0.f, dg = m < 3 ? acc[ai][1][m < 3 ? m + 1 : 3][n][i] : 0.f;
;                         const float pv = dpp_ror1(fr == 15 ? uv : xv), pg = dpp_ror1(fr == 15 ? ug : xg);
;                         const float nv = dpp_rol1(fr == 0 ? dv : xv), ng = dpp_rol1(fr == 0 ? dg : xg);
;                         const float yv = wv0[i] * pv + wv1[i] * xv + wv2[i] * nv + bv[i];
;                         const float yg = wg0[i] * pg + wg1[i] * xg + wg2[i] * ng + bg[i];
;                         r[i] = yg * sigmoidf_(yg) * yv;
;                     }
;                     st_bf4(ACT + (size_t)(u.pm * BM + ai * HALF + wr * 64 + m * 16 + fr) * FF + cv, r);
	v_pk_mul_f32 v[18:19], v[22:23], v[150:151]
	v_pk_mul_f32 v[8:9], v[12:13], v[148:149]
	v_pk_mul_f32 v[10:11], v[14:15], v[150:151]
	v_pk_mul_f32 v[0:1], v[4:5], v[148:149]
	v_pk_mul_f32 v[2:3], v[6:7], v[150:151]
	v_pk_fma_f32 v[24:25], v[144:145], v[216:217], v[24:25]
	v_pk_fma_f32 v[26:27], v[146:147], v[218:219], v[26:27]
	v_pk_fma_f32 v[16:17], v[144:145], v[28:29], v[16:17]
	v_pk_fma_f32 v[18:19], v[146:147], v[30:31], v[18:19]
	v_pk_fma_f32 v[8:9], v[144:145], v[20:21], v[8:9]
	v_pk_fma_f32 v[10:11], v[146:147], v[22:23], v[10:11]
	v_pk_fma_f32 v[0:1], v[144:145], v[12:13], v[0:1]
	v_pk_fma_f32 v[2:3], v[146:147], v[14:15], v[2:3]
	v_pk_fma_f32 v[24:25], v[208:209], v[20:21], v[24:25]
	v_pk_fma_f32 v[26:27], v[210:211], v[22:23], v[26:27]
	v_pk_fma_f32 v[16:17], v[208:209], v[12:13], v[16:17]
	v_pk_fma_f32 v[18:19], v[210:211], v[14:15], v[18:19]
	v_pk_fma_f32 v[8:9], v[208:209], v[4:5], v[8:9]
	v_pk_fma_f32 v[10:11], v[210:211], v[6:7], v[10:11]
	v_pk_fma_f32 v[0:1], v[208:209], v[220:221], v[0:1]
	v_pk_fma_f32 v[2:3], v[210:211], v[222:223], v[2:3]
	v_pk_add_f32 v[24:25], v[212:213], v[24:25]
	v_pk_add_f32 v[26:27], v[214:215], v[26:27]
	v_pk_add_f32 v[16:17], v[212:213], v[16:17]
	v_pk_add_f32 v[18:19], v[214:215], v[18:19]
	v_pk_add_f32 v[8:9], v[212:213], v[8:9]
	v_pk_add_f32 v[10:11], v[214:215], v[10:11]
	v_pk_add_f32 v[0:1], v[212:213], v[0:1]
	v_pk_add_f32 v[2:3], v[214:215], v[2:3]
	v_mul_f32_e32 v28, 0xbfb8aa3b, v176
	v_mul_f32_e32 v29, 0xbfb8aa3b, v177
	v_mul_f32_e32 v30, 0xbfb8aa3b, v178
	v_mul_f32_e32 v31, 0xbfb8aa3b, v179
	v_mul_f32_e32 v20, 0xbfb8aa3b, v180
	v_mul_f32_e32 v21, 0xbfb8aa3b, v181
	v_mul_f32_e32 v22, 0xbfb8aa3b, v182
	v_mul_f32_e32 v23, 0xbfb8aa3b, v183
	v_mul_f32_e32 v12, 0xbfb8aa3b, v184
	v_mul_f32_e32 v13, 0xbfb8aa3b, v185
	v_mul_f32_e32 v14, 0xbfb8aa3b, v186
	v_mul_f32_e32 v15, 0xbfb8aa3b, v187
	v_mul_f32_e32 v4, 0xbfb8aa3b, v224
	v_mul_f32_e32 v5, 0xbfb8aa3b, v225
	v_mul_f32_e32 v6, 0xbfb8aa3b, v226
	v_mul_f32_e32 v7, 0xbfb8aa3b, v227
	v_exp_f32_e32 v28, v28
	v_exp_f32_e32 v29, v29
	v_exp_f32_e32 v30, v30
	v_exp_f32_e32 v31, v31
	v_exp_f32_e32 v20, v20
	v_exp_f32_e32 v21, v21
	v_exp_f32_e32 v22, v22
	v_exp_f32_e32 v23, v23
	v_exp_f32_e32 v12, v12
	v_exp_f32_e32 v13, v13
	v_exp_f32_e32 v14, v14
	v_exp_f32_e32 v15, v15
	v_exp_f32_e32 v4, v4
	v_exp_f32_e32 v5, v5
	v_exp_f32_e32 v6, v6
	v_exp_f32_e32 v7, v7
	v_add_f32_e32 v28, 1.0, v28
	v_add_f32_e32 v29, 1.0, v29
	v_add_f32_e32 v30, 1.0, v30
	v_add_f32_e32 v31, 1.0, v31
	v_add_f32_e32 v20, 1.0, v20
	v_add_f32_e32 v21, 1.0, v21
	v_add_f32_e32 v22, 1.0, v22
	v_add_f32_e32 v23, 1.0, v23
	v_add_f32_e32 v12, 1.0, v12
	v_add_f32_e32 v13, 1.0, v13
	v_add_f32_e32 v14, 1.0, v14
	v_add_f32_e32 v15, 1.0, v15
	v_add_f32_e32 v4, 1.0, v4
	v_add_f32_e32 v5, 1.0, v5
	v_add_f32_e32 v6, 1.0, v6
	v_add_f32_e32 v7, 1.0, v7
	v_rcp_f32_e32 v28, v28
	v_rcp_f32_e32 v29, v29
	v_rcp_f32_e32 v30, v30
	v_rcp_f32_e32 v31, v31
	v_rcp_f32_e32 v20, v20
	v_rcp_f32_e32 v21, v21
	v_rcp_f32_e32 v22, v22
	v_rcp_f32_e32 v23, v23
	v_rcp_f32_e32 v12, v12
	v_rcp_f32_e32 v13, v13
	v_rcp_f32_e32 v14, v14
	v_rcp_f32_e32 v15, v15
	v_rcp_f32_e32 v4, v4
	v_rcp_f32_e32 v5, v5
	v_rcp_f32_e32 v6, v6
	v_rcp_f32_e32 v7, v7
	v_pk_mul_f32 v[176:177], v[176:177], v[28:29]
	v_pk_mul_f32 v[178:179], v[178:179], v[30:31]
	v_pk_mul_f32 v[180:181], v[180:181], v[20:21]
	v_pk_mul_f32 v[182:183], v[182:183], v[22:23]
	v_pk_mul_f32 v[184:185], v[184:185], v[12:13]
	v_pk_mul_f32 v[186:187], v[186:187], v[14:15]
	v_pk_mul_f32 v[224:225], v[224:225], v[4:5]
	v_pk_mul_f32 v[226:227], v[226:227], v[6:7]
	v_pk_mul_f32 v[176:177], v[24:25], v[176:177]
	v_pk_mul_f32 v[178:179], v[26:27], v[178:179]
	v_pk_mul_f32 v[180:181], v[16:17], v[180:181]
	v_pk_mul_f32 v[182:183], v[18:19], v[182:183]
	v_pk_mul_f32 v[184:185], v[8:9], v[184:185]
	v_pk_mul_f32 v[186:187], v[10:11], v[186:187]
	v_pk_mul_f32 v[224:225], v[0:1], v[224:225]
	v_pk_mul_f32 v[226:227], v[2:3], v[226:227]
	v_cvt_pk_bf16_f32 v28, v176, v177
	v_cvt_pk_bf16_f32 v29, v178, v179
	v_cvt_pk_bf16_f32 v20, v180, v181
	v_cvt_pk_bf16_f32 v21, v182, v183
	v_cvt_pk_bf16_f32 v12, v184, v185
	v_cvt_pk_bf16_f32 v13, v186, v187
	v_cvt_pk_bf16_f32 v4, v224, v225
	v_cvt_pk_bf16_f32 v5, v226, v227
	global_store_dwordx2 v174, v[28:29], s[0:1] offset:32
	v_add_u32_e32 v175, 0x2c00, v174
	global_store_dwordx2 v175, v[20:21], s[0:1] offset:32
	v_add_u32_e32 v175, 0x5800, v174
	global_store_dwordx2 v175, v[12:13], s[0:1] offset:32
	v_add_u32_e32 v175, 0x8400, v174
	global_store_dwordx2 v175, v[4:5], s[0:1] offset:32
	v_lshl_or_b32 v170, s16, 7, v204
	v_lshlrev_b32_e32 v171, 2, v170
	v_add_u32_e32 v172, 0x5800, v171
	global_load_dwordx4 v[230:233], v172, s[56:57]
	global_load_dwordx4 v[234:237], v172, s[12:13]
	global_load_dwordx4 v[238:241], v172, s[14:15]
	global_load_dwordx4 v[242:245], v172, s[58:59]
	global_load_dwordx4 v[246:249], v171, s[56:57]
	global_load_dwordx4 v[250:253], v171, s[12:13]
	s_mov_b32 s98, 1
	s_andn2_b64 vcc, exec, s[20:21]
	s_mov_b64 s[20:21], -1
	s_cbranch_vccnz .LBB0_1795
	s_andn2_b64 vcc, exec, s[2:3]
	s_cbranch_vccnz .LBB0_1794
	s_barrier
	s_branch .LBB0_1794
